# up-GEMM: last two rounds (322 units) handed out dynamically by atomic ticket
# baseline (speedup 1.0000x reference)
;     __device__ __forceinline__ bool next(int i, Unit& u) const { if (i > 0 || c >= nN) return false; u.pm = pm; u.pn = c; return true; }
;     __host__ __device__ bool next(int i, Unit& u) const {
;         const long L = (long)i * G + c; if (L >= nwg) return false;
;         int wgid = (int)L; { const int q = nwg / NXCD, r = nwg % NXCD, xcd = wgid % NXCD, off = wgid / NXCD; wgid = (xcd < r ? xcd * (q + 1) : r * (q + 1) + (xcd - r) * q) + off; }
;         const int nig = wgm * nN, gid = wgid / nig, fm = gid * wgm, gsz = (nM - fm) < wgm ? (nM - fm) : wgm;
;         u.pm = fm + ((wgid % nig) % gsz); u.pn = (wgid % nig) / gsz; return true;
; template <class Epi, class Sched, bool ALIGN_EPI = false, bool SP2 = false>
; __device__ __forceinline__ void gemm_phase(PG8_LAS unsigned char* lds, const Gemm g, const Sched& S, const Epi& E, int wid0) {
;     ...
;         const bool has_next = S.next(ui + 1, nxt);
.LBB0_547:
	s_add_i32 s84, s59, 1
	s_mul_i32 s2, s84, s50
	s_mul_hi_u32 s3, s84, s38
	s_add_i32 s3, s3, s2
	s_mul_i32 s2, s84, s38
	s_add_u32 s2, s2, s33
	s_addc_u32 s3, s3, s39
	s_cmp_lt_u32 s84, 10
	s_cbranch_scc1 .Ldyn_skip
	v_readlane_b32 s4, v255, 40
	s_cmp_lg_u32 s4, 0
	s_cbranch_scc1 .Ldyn_wait
	v_readlane_b32 s4, v255, 38
	v_readlane_b32 s5, v255, 39
	v_readlane_b32 s2, v255, 41
	s_nop 4
	s_load_dwordx2 s[4:5], s[4:5], 0x98
	s_lshl_b32 s2, s2, 2
	v_mov_b32_e32 v3, s2
	v_mov_b32_e32 v2, 1
	s_mov_b64 s[2:3], exec
	s_mov_b64 exec, 1
	s_waitcnt lgkmcnt(0)
	global_atomic_add v2, v3, v2, s[4:5] sc0
	s_waitcnt vmcnt(0)
	v_add_u32_e32 v2, 0xa00, v2
	v_mov_b32_e32 v3, 0x25f08
	ds_write_b32 v3, v2
	s_waitcnt lgkmcnt(0)
	s_mov_b64 exec, s[2:3]
